# MLA: short unit of each workgroup's last item moved to a dynamically claimed pool (longest first) so faster XCDs take more
# baseline (speedup 1.0000x reference)
; #define LAS __attribute__((address_space(3)))
; __global__ void __launch_bounds__(512) fwd_mega(Args a) {
;     extern __shared__ __attribute__((aligned(16))) unsigned char lds_raw[];
;     LAS unsigned char* lds = (LAS unsigned char*)lds_raw;
;     cg::grid_group grid = cg::this_grid();
;     const int tid = threadIdx.x, lane = tid & 63, wave = __builtin_amdgcn_readfirstlane(tid >> 6);
;     const int G = gridDim.x, bx = blockIdx.x;
;     const int vcu = (G % 8 == 0) ? (bx % 8) * (G / 8) + bx / 8 : bx;
;     unsigned char* ws = a.ws;
_Z8fwd_mega4Args:
	s_load_dwordx16 s[72:87], s[0:1], 0x0
	s_load_dwordx8 s[24:31], s[0:1], 0x80
	s_load_dwordx4 s[52:55], s[0:1], 0xa0
	s_load_dword s3, s[0:1], 0xb0
	s_add_u32 s58, s0, 0xb0
	s_mov_b32 s60, s2
	s_addc_u32 s59, s1, 0
	v_and_b32_e32 v162, 0x3ff, v0
	s_waitcnt lgkmcnt(0)
	s_cmp_eq_u32 s60, 0
	s_cbranch_scc0 .Lsm_init_done
	v_and_b32_e32 v254, 7, v162
	v_lshlrev_b32_e32 v254, 8, v254
	v_add_u32_e32 v254, 0x400, v254
	v_mov_b32_e32 v255, 0
	global_store_dword v254, v255, s[52:53]
	v_mov_b32_e32 v254, 0xc00
	global_store_dword v254, v255, s[52:53]
	v_mov_b32_e32 v254, 0xd00
	global_store_dword v254, v255, s[52:53]

; #define LAS __attribute__((address_space(3)))
; template <bool MLA> __device__ __forceinline__ void attn_unit(const AttnP& P, int b, int hh, int qb, LAS char* lds) {
;     ...
;     const int tid = threadIdx.x, wid = __builtin_amdgcn_readfirstlane(tid >> 6), lane = tid & 63, r32 = lane & 31, hi = lane >> 5;
;     LAS char* V_lds = lds; LAS char* K_lds = lds + 2 * VBYTES;
;     LAS float* ws = (LAS float*)(lds + 2 * VBYTES + 2 * KBYTES) + wid * 64; LAS float* li_l = ws; LAS float* al_l = ws + 32;
;     LAS float* bias_l = (LAS float*)(lds + 2 * VBYTES + 2 * KBYTES + 2048);
;     const int q0 = qb * 256; const size_t rowbase = (size_t)b * SEQ;
;     const int jt0 = MLA ? 0 : (q0 == 0 ? 0 : -2);
;     const int NT = MLA ? 4 * qb + 4 : 4 - jt0;
;     const int kbase0 = MLA ? 0 : q0 + 64 * jt0;
;     const int qlo = q0 + wid * 32, qm = qlo + r32 - 4 * hi;
;     bf16x8 qr[NQF];
;     const size_t qrow = rowbase + qlo + r32;
;     if constexpr (MLA) {
; #pragma unroll
;         for (int d0 = 0; d0 < 8; ++d0) qr[d0] = *(const bf16x8*)(P.QN + qrow * 2048 + hh * 128 + d0 * 16 + hi * 8);
; #pragma unroll
;         for (int d0 = 0; d0 < 4; ++d0) qr[8 + d0] = *(const bf16x8*)(P.QR + qrow * 1024 + hh * 64 + d0 * 16 + hi * 8);
;     } else {
; #pragma unroll
;         for (int d0 = 0; d0 < 4; ++d0) qr[d0] = *(const bf16x8*)(P.QS + qrow * 2048 + hh * 64 + d0 * 16 + hi * 8);
;         if (tid < 128) bias_l[tid] = P.rel[(int)T5B[tid] * 32 + hh] * (1.0f / SCALE);
;     }
;     bf16x8 sk0, sv0;
;     const int sr8 = tid >> 3, ch8 = tid & 7;
;     const bf16_t* Kg; const bf16_t* Vg; const bf16_t* Rg = nullptr;
;     unsigned okA = 0, okB = 0, orp = 0, ovA = 0, ovB = 0;
;     if constexpr (MLA) {
;         Kg = P.KN + rowbase * 2048 + hh * 128; Vg = P.V + rowbase * 2048 + hh * 128; Rg = P.KR + rowbase * 64;
;         { const int rA = 4 * wid + (lane >> 4), rB = rA + 32, cp = lane & 15; okA = (unsigned)(rA * 2048 + ((cp ^ (rA & 7)) << 3)); okB = (unsigned)(rB * 2048 + ((cp ^ (rB & 7)) << 3)); }
;         { const int rr = 8 * wid + (lane >> 3), cp = lane & 7; orp = (unsigned)(rr * 64 + ((cp ^ (rr & 7)) << 3)); }
;         { const int stA = 2 * wid + (lane >> 5), stB = stA + 16; const int kl = (lane & 31) >> 2, c8 = 8 * (lane & 3);
;           const int kkA = (stA >> 2) * 8 + kl, kkB = (stB >> 2) * 8 + kl;
.LBB0_301:
	s_cmp_lt_i32 s54, 4
	s_cselect_b64 s[4:5], -1, 0
	s_and_b64 s[44:45], s[4:5], s[0:1]
	s_andn2_b64 vcc, exec, s[44:45]
	s_cbranch_vccnz .LBB0_682
	s_cmpk_gt_i32 s2, 0x3ff
	v_lshrrev_b32_e32 v1, 5, v206
	v_and_b32_e32 v198, 7, v162
	v_lshrrev_b32_e32 v200, 2, v162
	v_lshlrev_b32_e32 v147, 3, v162
	v_lshlrev_b32_e32 v199, 1, v162
	v_cmp_gt_u32_e64 s[0:1], 32, v206
	v_and_b32_e32 v151, 1, v162
	s_cbranch_scc1 .LBB0_597
	v_readfirstlane_b32 s4, v162
	s_nop 3
	s_lshr_b32 s4, s4, 6
	s_lshl_b32 s5, s4, 10
	s_add_u32 s6, s52, 0x1e000000
	s_addc_u32 s7, s53, 0
	s_add_u32 s8, s52, 0x26000000
	s_addc_u32 s9, s53, 0
	s_add_u32 s12, s52, 0x2a000000
	s_addc_u32 s13, s53, 0
	s_add_u32 s14, s52, 0x13c00000
	s_addc_u32 s15, s53, 0
	s_add_u32 s16, s52, 0x32000000
	s_addc_u32 s17, s53, 0
	s_mov_b32 s72, 0x4138aa3b
	v_mov_b32_e32 v245, 0xff800000
	v_mov_b32_e32 v248, 0
	v_and_b32_e32 v221, 15, v206
	v_lshrrev_b32_e32 v222, 4, v206
	v_lshrrev_b32_e32 v223, 1, v221
	v_xor_b32_e32 v223, v223, v222
	v_lshlrev_b32_e32 v223, 4, v223
	v_lshl_or_b32 v224, v221, 7, v223
	v_xor_b32_e32 v225, 64, v224
	v_lshrrev_b32_e32 v223, 1, v222
	v_lshlrev_b32_e32 v223, 11, v223
	v_and_b32_e32 v220, 1, v222
	v_lshl_or_b32 v223, v220, 8, v223
	v_lshrrev_b32_e32 v226, 2, v221
	v_lshl_or_b32 v223, v226, 6, v223
	v_and_b32_e32 v226, 3, v221
	v_lshl_or_b32 v223, v226, 3, v223
	v_lshlrev_b32_e32 v220, 5, v220
	v_or_b32_e32 v226, v223, v220
	v_xor_b32_e32 v220, 32, v220
	v_or_b32_e32 v227, v223, v220
	v_lshlrev_b32_e32 v223, 2, v222
	v_sub_u32_e32 v243, v221, v223
	v_xor_b32_e32 v246, 16, v206
	v_lshlrev_b32_e32 v246, 2, v246
	v_xor_b32_e32 v247, 32, v206
	v_lshlrev_b32_e32 v247, 2, v247
	v_lshlrev_b32_e32 v223, 4, v222
	v_lshl_or_b32 v237, v221, 12, v223
	v_add_u32_e32 v238, 0x10000, v237
	v_lshl_or_b32 v239, v221, 11, v223
	v_add_u32_e32 v240, 0x8000, v239
	v_lshlrev_b32_e32 v223, 3, v222
	v_lshl_or_b32 v241, v221, 12, v223
	v_add_u32_e32 v242, 0x10000, v241
	v_bfe_u32 v221, v162, 4, 3
	v_bitop3_b32 v221, v221, v162, 7 bitop3:0x78
	v_lshlrev_b32_e32 v221, 4, v221
	v_lshrrev_b32_e32 v222, 3, v162
	v_lshl_or_b32 v232, v222, 12, v221
	v_add_u32_e32 v233, 0x80, v232
	v_lshl_or_b32 v234, v222, 7, v221
	v_bfe_u32 v221, v206, 2, 3
	v_lshrrev_b32_e32 v222, 2, v221
	v_lshlrev_b32_e32 v222, 1, v222
	v_and_b32_e32 v223, 3, v206
	v_xor_b32_e32 v223, v223, v222
	v_lshlrev_b32_e32 v223, 4, v223
	v_lshrrev_b32_e32 v222, 5, v206
	v_lshl_or_b32 v223, v222, 6, v223
	s_lshr_b32 s36, s4, 1
	s_lshl_b32 s36, s36, 15
	s_and_b32 s37, s4, 1
	s_lshl_b32 s37, s37, 7
	s_add_i32 s36, s36, s37
	v_lshl_or_b32 v223, v221, 12, v223
	v_add_u32_e32 v235, s36, v223
	v_add_u32_e32 v236, 0x20000, v235
	s_mov_b32 s28, s2
	s_mov_b32 s98, 0
	v_mov_b32_e32 v250, 0x14000

; #define LAS __attribute__((address_space(3)))
; __device__ __forceinline__ int crow(int r, int hi) { return (r & 3) + 8 * (r >> 2) + 4 * hi; }
; __device__ __forceinline__ unsigned cvtpk(float lo, float hi) { f32x2_cv v = {lo, hi}; bf16x2_cv b = __builtin_convertvector(v, bf16x2_cv); return __builtin_bit_cast(unsigned, b); }
; template <bool MLA> __device__ __forceinline__ void attn_unit(const AttnP& P, int b, int hh, int qb, LAS char* lds) {
;     ...
;     if (hi == 0) li_l[r32] = l_reg; asm volatile("s_waitcnt lgkmcnt(0)" ::: "memory");
;     bf16_t* Ow = (MLA ? P.QN + (rowbase + qlo) * 2048 + hh * 128 : P.QS + (rowbase + qlo) * 2048 + hh * 64);
; #pragma unroll
;     for (int r = 0; r < 16; ++r) { const int orow = crow(r, hi); const float rl = __builtin_amdgcn_rcpf(li_l[orow]);
; #pragma unroll
;         for (int d0 = 0; d0 < NCB; ++d0) { const float v = o[d0][r] * rl; const float vn = __shfl_xor(v, 1);
;             if ((r32 & 1) == 0) *(unsigned*)(Ow + (size_t)orow * 2048 + d0 * 32 + r32) = cvtpk(v, vn); } }
; __global__ void __launch_bounds__(512) fwd_mega(Args a) {
;     ...
;         for (int it = vcu; it < 1024; it += G) { const int bh = it >> 5, s = it & 31;
;             att::attn_unit<true>(P, bh >> 4, bh & 15, 63 - s, (LAS char*)lds);
;             att::attn_unit<true>(P, bh >> 4, bh & 15, s, (LAS char*)lds); }
.Lm16_tile_end:
	s_waitcnt vmcnt(0) lgkmcnt(0)
	s_barrier
	s_add_u32 s41, s41, 1
	s_add_u32 s42, s42, 64
	s_cmp_lt_u32 s41, s40
	s_cbranch_scc1 .Lm16_tile
	s_nop 7
	ds_bpermute_b32 v221, v246, v216
	s_waitcnt lgkmcnt(0)
	v_add_f32_e32 v216, v216, v221
	ds_bpermute_b32 v221, v247, v216
	s_waitcnt lgkmcnt(0)
	v_add_f32_e32 v216, v216, v221
	v_rcp_f32_e32 v216, v216
	ds_bpermute_b32 v221, v246, v217
	s_waitcnt lgkmcnt(0)
	v_add_f32_e32 v217, v217, v221
	ds_bpermute_b32 v221, v247, v217
	s_waitcnt lgkmcnt(0)
	v_add_f32_e32 v217, v217, v221
	v_rcp_f32_e32 v217, v217
	s_nop 0
	v_mul_f32_e32 v2, v2, v216
	v_mul_f32_e32 v3, v3, v216
	v_mul_f32_e32 v4, v4, v216
	v_mul_f32_e32 v5, v5, v216
	v_cvt_pk_bf16_f32 v2, v2, v3
	v_cvt_pk_bf16_f32 v3, v4, v5
	global_store_dwordx2 v241, v[2:3], s[66:67] offset:0
	v_mul_f32_e32 v6, v6, v217
	v_mul_f32_e32 v7, v7, v217
	v_mul_f32_e32 v8, v8, v217
	v_mul_f32_e32 v9, v9, v217
	v_cvt_pk_bf16_f32 v6, v6, v7
	v_cvt_pk_bf16_f32 v7, v8, v9
	global_store_dwordx2 v242, v[6:7], s[66:67] offset:0
	v_mul_f32_e32 v10, v10, v216
	v_mul_f32_e32 v11, v11, v216
	v_mul_f32_e32 v12, v12, v216
	v_mul_f32_e32 v13, v13, v216
	v_cvt_pk_bf16_f32 v10, v10, v11
	v_cvt_pk_bf16_f32 v11, v12, v13
	global_store_dwordx2 v241, v[10:11], s[66:67] offset:32
	v_mul_f32_e32 v14, v14, v217
	v_mul_f32_e32 v15, v15, v217
	v_mul_f32_e32 v16, v16, v217
	v_mul_f32_e32 v17, v17, v217
	v_cvt_pk_bf16_f32 v14, v14, v15
	v_cvt_pk_bf16_f32 v15, v16, v17
	global_store_dwordx2 v242, v[14:15], s[66:67] offset:32
	v_mul_f32_e32 v18, v18, v216
	v_mul_f32_e32 v19, v19, v216
	v_mul_f32_e32 v20, v20, v216
	v_mul_f32_e32 v21, v21, v216
	v_cvt_pk_bf16_f32 v18, v18, v19
	v_cvt_pk_bf16_f32 v19, v20, v21
	global_store_dwordx2 v241, v[18:19], s[66:67] offset:64
	v_mul_f32_e32 v22, v22, v217
	v_mul_f32_e32 v23, v23, v217
	v_mul_f32_e32 v24, v24, v217
	v_mul_f32_e32 v25, v25, v217
	v_cvt_pk_bf16_f32 v22, v22, v23
	v_cvt_pk_bf16_f32 v23, v24, v25
	global_store_dwordx2 v242, v[22:23], s[66:67] offset:64
	v_mul_f32_e32 v26, v26, v216
	v_mul_f32_e32 v27, v27, v216
	v_mul_f32_e32 v28, v28, v216
	v_mul_f32_e32 v29, v29, v216
	v_cvt_pk_bf16_f32 v26, v26, v27
	v_cvt_pk_bf16_f32 v27, v28, v29
	global_store_dwordx2 v241, v[26:27], s[66:67] offset:96
	v_mul_f32_e32 v30, v30, v217
	v_mul_f32_e32 v31, v31, v217
	v_mul_f32_e32 v32, v32, v217
	v_mul_f32_e32 v33, v33, v217
	v_cvt_pk_bf16_f32 v30, v30, v31
	v_cvt_pk_bf16_f32 v31, v32, v33
	global_store_dwordx2 v242, v[30:31], s[66:67] offset:96
	v_mul_f32_e32 v34, v34, v216
	v_mul_f32_e32 v35, v35, v216
	v_mul_f32_e32 v36, v36, v216
	v_mul_f32_e32 v37, v37, v216
	v_cvt_pk_bf16_f32 v34, v34, v35
	v_cvt_pk_bf16_f32 v35, v36, v37
	global_store_dwordx2 v241, v[34:35], s[66:67] offset:128
	v_mul_f32_e32 v38, v38, v217
	v_mul_f32_e32 v39, v39, v217
	v_mul_f32_e32 v40, v40, v217
	v_mul_f32_e32 v41, v41, v217
	v_cvt_pk_bf16_f32 v38, v38, v39
	v_cvt_pk_bf16_f32 v39, v40, v41
	global_store_dwordx2 v242, v[38:39], s[66:67] offset:128
	v_mul_f32_e32 v42, v42, v216
	v_mul_f32_e32 v43, v43, v216
	v_mul_f32_e32 v44, v44, v216
	v_mul_f32_e32 v45, v45, v216
	v_cvt_pk_bf16_f32 v42, v42, v43
	v_cvt_pk_bf16_f32 v43, v44, v45
	global_store_dwordx2 v241, v[42:43], s[66:67] offset:160
	v_mul_f32_e32 v46, v46, v217
	v_mul_f32_e32 v47, v47, v217
	v_mul_f32_e32 v48, v48, v217
	v_mul_f32_e32 v49, v49, v217
	v_cvt_pk_bf16_f32 v46, v46, v47
	v_cvt_pk_bf16_f32 v47, v48, v49
	global_store_dwordx2 v242, v[46:47], s[66:67] offset:160
	v_mul_f32_e32 v50, v50, v216
	v_mul_f32_e32 v51, v51, v216
	v_mul_f32_e32 v52, v52, v216
	v_mul_f32_e32 v53, v53, v216
	v_cvt_pk_bf16_f32 v50, v50, v51
	v_cvt_pk_bf16_f32 v51, v52, v53
	global_store_dwordx2 v241, v[50:51], s[66:67] offset:192
	v_mul_f32_e32 v54, v54, v217
	v_mul_f32_e32 v55, v55, v217
	v_mul_f32_e32 v56, v56, v217
	v_mul_f32_e32 v57, v57, v217
	v_cvt_pk_bf16_f32 v54, v54, v55
	v_cvt_pk_bf16_f32 v55, v56, v57
	global_store_dwordx2 v242, v[54:55], s[66:67] offset:192
	v_mul_f32_e32 v58, v58, v216
	v_mul_f32_e32 v59, v59, v216
	v_mul_f32_e32 v60, v60, v216
	v_mul_f32_e32 v61, v61, v216
	v_cvt_pk_bf16_f32 v58, v58, v59
	v_cvt_pk_bf16_f32 v59, v60, v61
	global_store_dwordx2 v241, v[58:59], s[66:67] offset:224
	v_mul_f32_e32 v62, v62, v217
	v_mul_f32_e32 v63, v63, v217
	v_mul_f32_e32 v64, v64, v217
	v_mul_f32_e32 v65, v65, v217
	v_cvt_pk_bf16_f32 v62, v62, v63
	v_cvt_pk_bf16_f32 v63, v64, v65
	global_store_dwordx2 v242, v[62:63], s[66:67] offset:224
	s_cmp_lg_u32 s98, 0
	s_cbranch_scc1 .Lm16_claim
	s_add_u32 s29, s29, 1
	s_cmp_lt_u32 s29, 2
	s_cbranch_scc0 .Lm16_adv
	s_add_u32 s36, s28, s3
	s_cmp_lt_u32 s36, 0x400
	s_cbranch_scc1 .Lm16_unit
; template <bool MLA> __device__ __forceinline__ void attn_unit(const AttnP& P, int b, int hh, int qb, LAS char* lds) {
;     ...
;     const int tid = threadIdx.x, wid = __builtin_amdgcn_readfirstlane(tid >> 6), lane = tid & 63, r32 = lane & 31, hi = lane >> 5;
;     LAS char* V_lds = lds; LAS char* K_lds = lds + 2 * VBYTES;
;     LAS float* ws = (LAS float*)(lds + 2 * VBYTES + 2 * KBYTES) + wid * 64; LAS float* li_l = ws; LAS float* al_l = ws + 32;
;     LAS float* bias_l = (LAS float*)(lds + 2 * VBYTES + 2 * KBYTES + 2048);
;     const int q0 = qb * 256; const size_t rowbase = (size_t)b * SEQ;
;     const int jt0 = MLA ? 0 : (q0 == 0 ? 0 : -2);
;     const int NT = MLA ? 4 * qb + 4 : 4 - jt0;
;     const int kbase0 = MLA ? 0 : q0 + 64 * jt0;
;     const int qlo = q0 + wid * 32, qm = qlo + r32 - 4 * hi;
;     bf16x8 qr[NQF];
;     const size_t qrow = rowbase + qlo + r32;
;     if constexpr (MLA) {
; #pragma unroll
;         for (int d0 = 0; d0 < 8; ++d0) qr[d0] = *(const bf16x8*)(P.QN + qrow * 2048 + hh * 128 + d0 * 16 + hi * 8);
; #pragma unroll
;         for (int d0 = 0; d0 < 4; ++d0) qr[8 + d0] = *(const bf16x8*)(P.QR + qrow * 1024 + hh * 64 + d0 * 16 + hi * 8);
;     } else {
; #pragma unroll
;         for (int d0 = 0; d0 < 4; ++d0) qr[d0] = *(const bf16x8*)(P.QS + qrow * 2048 + hh * 64 + d0 * 16 + hi * 8);
;         if (tid < 128) bias_l[tid] = P.rel[(int)T5B[tid] * 32 + hh] * (1.0f / SCALE);
;     }
;     bf16x8 sk0, sv0;
;     const int sr8 = tid >> 3, ch8 = tid & 7;
;     const bf16_t* Kg; const bf16_t* Vg; const bf16_t* Rg = nullptr;
;     unsigned okA = 0, okB = 0, orp = 0, ovA = 0, ovB = 0;
;     if constexpr (MLA) {
;         Kg = P.KN + rowbase * 2048 + hh * 128; Vg = P.V + rowbase * 2048 + hh * 128; Rg = P.KR + rowbase * 64;
;         { const int rA = 4 * wid + (lane >> 4), rB = rA + 32, cp = lane & 15; okA = (unsigned)(rA * 2048 + ((cp ^ (rA & 7)) << 3)); okB = (unsigned)(rB * 2048 + ((cp ^ (rB & 7)) << 3)); }
; __global__ void __launch_bounds__(512) fwd_mega(Args a) {
;     ...
;         for (int it = vcu; it < 1024; it += G) { const int bh = it >> 5, s = it & 31;
;             att::attn_unit<true>(P, bh >> 4, bh & 15, 63 - s, (LAS char*)lds);
;             att::attn_unit<true>(P, bh >> 4, bh & 15, s, (LAS char*)lds); }
;     ...
;         for (int it = vcu; it < 4096; it += G) { const int qb = it & 63, hq = (it >> 6) & 31, b = it >> 11;
.Lm16_adv:
	s_add_u32 s28, s28, s3
	s_cmp_lt_u32 s28, 0x400
	s_cbranch_scc1 .Lm16_item
	s_mov_b32 s98, 1
.Lm16_claim:
	s_waitcnt lgkmcnt(0)
	s_barrier
	s_cmp_eq_u32 s4, 0
	s_cbranch_scc0 .Lm16_cl1
	s_mov_b64 s[100:101], exec
	s_mov_b64 exec, 1
	v_mov_b32_e32 v251, 0xd00
	v_mov_b32_e32 v252, 1
	global_atomic_add v249, v251, v252, s[52:53] sc0
	s_mov_b64 exec, s[100:101]
	s_waitcnt vmcnt(0)
	v_readfirstlane_b32 s36, v249
	s_nop 3
	v_mov_b32_e32 v251, s36
	ds_write_b32 v250, v251
.Lm16_cl1:
	s_waitcnt lgkmcnt(0)
	s_barrier
	ds_read_b32 v251, v250
	s_waitcnt lgkmcnt(0)
	v_readfirstlane_b32 s36, v251
	s_nop 3
	s_cmp_lt_u32 s36, s3
	s_cbranch_scc0 .Lm16_pool_done
	s_cmp_eq_u32 s3, 0x100
	s_cbranch_scc0 .Lm16_lin
	s_lshr_b32 s37, s36, 3
	s_sub_u32 s37, 31, s37
	s_and_b32 s36, s36, 7
	s_lshl_b32 s36, s36, 5
	s_add_u32 s36, s36, s37
.Lm16_lin:
	s_sub_u32 s28, 0x400, s3
	s_add_u32 s28, s28, s36
	s_mov_b32 s29, 1
	s_branch .Lm16_unit
.Lm16_pool_done:
	s_waitcnt vmcnt(0) lgkmcnt(0)
.LBB0_597:
	v_readlane_b32 s64, v253, 0
	s_cmpk_gt_i32 s2, 0xfff
	v_readlane_b32 s68, v253, 4
	v_readlane_b32 s69, v253, 5
	v_readlane_b32 s70, v253, 6
	v_readlane_b32 s71, v253, 7
	v_readlane_b32 s65, v253, 1
	v_readlane_b32 s66, v253, 2
	v_readlane_b32 s67, v253, 3
	v_readlane_b32 s72, v253, 8
	v_readlane_b32 s73, v253, 9
	v_readlane_b32 s74, v253, 10
	v_readlane_b32 s75, v253, 11
	v_readlane_b32 s76, v253, 12
	v_readlane_b32 s77, v253, 13
	v_readlane_b32 s78, v253, 14
	v_readlane_b32 s79, v253, 15
	s_cbranch_scc1 .LBB0_682
	v_readlane_b32 s46, v253, 44
	v_readlane_b32 s47, v253, 45
	v_readlane_b32 s48, v253, 46
	v_readlane_b32 s49, v253, 47
	v_readfirstlane_b32 s4, v162
	s_nop 3
	s_lshr_b32 s4, s4, 6
	s_mov_b32 s29, 0x3e38aa3b
	v_mov_b32_e32 v238, 0xff800000
	v_and_b32_e32 v240, 15, v206
	v_lshrrev_b32_e32 v241, 4, v206
	v_and_b32_e32 v242, 7, v240
	v_xor_b32_e32 v242, v242, v241
	v_lshlrev_b32_e32 v242, 4, v242
	v_lshl_or_b32 v228, v240, 7, v242
	v_xor_b32_e32 v229, 64, v228
	v_add_u32_e32 v228, 49152, v228
	v_add_u32_e32 v229, 49152, v229
	v_and_b32_e32 v242, 1, v241
	v_lshrrev_b32_e32 v243, 1, v241
	v_lshlrev_b32_e32 v243, 8, v243
	v_lshl_or_b32 v243, v242, 10, v243
	v_lshrrev_b32_e32 v244, 2, v240
	v_lshl_or_b32 v243, v244, 6, v243
	v_and_b32_e32 v244, 3, v240
	v_lshl_or_b32 v243, v244, 3, v243
	v_lshlrev_b32_e32 v242, 5, v242
	v_or_b32_e32 v230, v243, v242
	v_xor_b32_e32 v242, 32, v242
	v_or_b32_e32 v231, v243, v242
	v_lshlrev_b32_e32 v242, 2, v241
	v_sub_u32_e32 v235, v240, v242
	v_lshlrev_b32_e32 v232, 2, v235
	v_add_u32_e32 v232, 98288, v232
	v_xor_b32_e32 v236, 16, v206
	v_lshlrev_b32_e32 v236, 2, v236
	v_xor_b32_e32 v237, 32, v206
	v_lshlrev_b32_e32 v237, 2, v237
	v_lshlrev_b32_e32 v242, 4, v241
	v_lshl_or_b32 v233, v240, 12, v242
	v_add_u32_e32 v196, 0x10000, v233
	v_lshlrev_b32_e32 v242, 3, v241
	v_lshl_or_b32 v234, v240, 12, v242
	v_add_u32_e32 v197, 0x10000, v234
	v_lshrrev_b32_e32 v240, 3, v162
	v_and_b32_e32 v241, 7, v162
	v_lshlrev_b32_e32 v242, 4, v241
	v_lshl_or_b32 v147, v240, 9, v242
	v_and_b32_e32 v242, 7, v240
	v_xor_b32_e32 v242, v242, v241
	v_lshlrev_b32_e32 v242, 4, v242
	v_lshl_or_b32 v148, v240, 7, v242
	v_add_u32_e32 v148, 49152, v148
	v_bfe_u32 v242, v240, 2, 1
	v_bfe_u32 v243, v240, 3, 1
	v_and_b32_e32 v244, 3, v240
	v_lshl_or_b32 v244, v243, 2, v244
	v_lshrrev_b32_e32 v245, 4, v240
	v_lshl_or_b32 v245, v245, 1, v242
	v_lshrrev_b32_e32 v246, 2, v241
	v_lshl_or_b32 v245, v245, 1, v246
	v_lshlrev_b32_e32 v245, 9, v245
	v_lshl_or_b32 v245, v244, 6, v245
	v_and_b32_e32 v246, 3, v241
	v_lshlrev_b32_e32 v246, 4, v246
	v_lshlrev_b32_e32 v242, 5, v242
	v_xor_b32_e32 v246, v246, v242
	v_or_b32_e32 v149, v245, v246
	s_getpc_b64 s[100:101]
	s_add_u32 s100, s100, _ZN3attL3T5BE@rel32@lo+4
	s_addc_u32 s101, s101, _ZN3attL3T5BE@rel32@hi+12
	v_mov_b32_e32 v150, 0
	v_cmp_gt_u32_e32 vcc, 0x80, v162
	s_nop 1
	s_and_saveexec_b64 s[0:1], vcc
	global_load_ubyte v150, v162, s[100:101]
	s_or_b64 exec, exec, s[0:1]
	v_lshlrev_b32_e32 v152, 2, v162
	v_add_u32_e32 v152, 98304, v152
	v_and_b32_e32 v153, 7, v206
	v_lshlrev_b32_e32 v153, 2, v153
	s_waitcnt vmcnt(0)
	v_lshlrev_b32_e32 v150, 7, v150
	v_mov_b32_e32 v248, 0x1a000
	s_cmp_eq_u32 s4, 0
	s_cbranch_scc0 .Lsw_na0
	s_mov_b64 s[100:101], exec
	s_mov_b64 exec, 1
	v_mov_b32_e32 v163, 0xc00
	v_mov_b32_e32 v1, 1
	global_atomic_add v239, v163, v1, s[52:53] sc0
	s_mov_b64 exec, s[100:101]
